# v11 + attention score max tree rewritten as 8 v_max3 (drops redundant canonicalizing v_max)
# speedup vs baseline: 1.0073x; 1.0051x over previous
; #define MFMA16(a, b, c) __builtin_amdgcn_mfma_f32_16x16x32_bf16((a), (b), (c), 0, 0, 0)
; DI void attn_phase(const Params& p, unsigned char* smem) {
;     ...
;                         for (int kk = 0; kk < 4; ++kk) {
;                             st[kk] = (f32x4){nm, nm, nm, nm};
; #pragma unroll
;                             for (int s = 0; s < 3; ++s) st[kk] = MFMA16(kf[kk][s], qf[qs][s], st[kk]);
;                         }
;                         float mx = fmaxf(fmaxf(st[0][0], st[0][1]), fmaxf(st[0][2], st[0][3]));
; #pragma unroll
;                         for (int kk = 1; kk < 4; ++kk) mx = fmaxf(mx, fmaxf(fmaxf(st[kk][0], st[kk][1]), fmaxf(st[kk][2], st[kk][3])));
;                         const bool first = (st_ == 0 && hf == 0);
;                         if (first || __any(mx > 6.f)) {
;                             mx = fmaxf(mx, __shfl_xor(mx, 16)); mx = fmaxf(mx, __shfl_xor(mx, 32));
;                             const float shift = first ? mx : fmaxf(mx, 0.f);
;                             const float al = first ? 1.f : __builtin_amdgcn_exp2f(-shift);
;                             mrow[qs] += shift; lrow[qs] *= al;
; #pragma unroll
;                             for (int dt = 0; dt < 4; ++dt) ot[dt][qs] *= al;
; #pragma unroll
;                             for (int kk = 0; kk < 4; ++kk)
; #pragma unroll
;                                 for (int e = 0; e < 4; ++e) st[kk][e] -= shift;
;                         }
.LBB0_929:
	s_or_b64 exec, exec, s[0:1]
	v_cmp_lt_i32_e32 vcc, 1, v230
	s_and_saveexec_b64 s[0:1], vcc
	s_cbranch_execz .LBB0_935
	v_xor_b32_e32 v132, 0x80000000, v203
	v_mov_b32_e32 v133, v132
	v_mov_b32_e32 v134, v132
	v_mov_b32_e32 v135, v132
	ds_read_b128 v[112:115], v229 offset:14336
	ds_read_b128 v[116:119], v229 offset:14400
	ds_read_b128 v[120:123], v229 offset:14464
	ds_read_b128 v[100:103], v229 offset:17920
	ds_read_b128 v[104:107], v229 offset:17984
	ds_read_b128 v[108:111], v229 offset:18048
	ds_read_b128 v[96:99], v229 offset:21504
	ds_read_b128 v[92:95], v229 offset:21568
	ds_read_b128 v[88:91], v229 offset:21632
	ds_read_b128 v[84:87], v229 offset:25088
	ds_read_b128 v[80:83], v229 offset:25152
	ds_read_b128 v[76:79], v229 offset:25216
	s_waitcnt lgkmcnt(11)
	v_mfma_f32_16x16x32_bf16 v[124:127], v[112:115], v[4:7], v[132:135]
	s_waitcnt lgkmcnt(8)
	v_mfma_f32_16x16x32_bf16 v[128:131], v[100:103], v[4:7], v[132:135]
	v_mfma_f32_16x16x32_bf16 v[124:127], v[116:119], v[0:3], v[124:127]
	s_waitcnt lgkmcnt(5)
	v_mfma_f32_16x16x32_bf16 v[136:139], v[96:99], v[4:7], v[132:135]
	s_waitcnt lgkmcnt(2)
	v_mfma_f32_16x16x32_bf16 v[132:135], v[84:87], v[4:7], v[132:135]
	v_mfma_f32_16x16x32_bf16 v[128:131], v[104:107], v[0:3], v[128:131]
	v_mfma_f32_16x16x32_bf16 v[124:127], v[120:123], v[12:15], v[124:127]
	s_waitcnt lgkmcnt(1)
	v_mfma_f32_16x16x32_bf16 v[132:135], v[80:83], v[0:3], v[132:135]
	v_mfma_f32_16x16x32_bf16 v[136:139], v[92:95], v[0:3], v[136:139]
	v_mfma_f32_16x16x32_bf16 v[128:131], v[108:111], v[12:15], v[128:131]
	s_waitcnt lgkmcnt(0)
	v_mfma_f32_16x16x32_bf16 v[144:147], v[76:79], v[12:15], v[132:135]
	s_nop 3
	v_max3_f32 v132, v124, v125, v126
	v_mfma_f32_16x16x32_bf16 v[138:141], v[88:91], v[12:15], v[136:139]
	v_max3_f32 v133, v127, v128, v129
	v_max3_f32 v132, v132, v130, v131
	v_max3_f32 v134, v144, v145, v146
	v_max3_f32 v132, v132, v133, v134
	s_nop 3
	v_max3_f32 v133, v138, v139, v140
	v_max3_f32 v132, v132, v133, v141
	v_max_f32_e32 v132, v132, v147
	v_cmp_lt_f32_e32 vcc, s34, v132
	s_cbranch_vccz .LBB0_932
	v_and_b32_e32 v134, 64, v251
	v_xor_b32_e32 v133, 16, v251
	v_add_u32_e32 v134, 64, v134
	v_cmp_lt_i32_e32 vcc, v133, v134
	s_nop 1
	v_cndmask_b32_e32 v133, v251, v133, vcc
	v_lshlrev_b32_e32 v133, 2, v133
	ds_bpermute_b32 v133, v133, v132
	v_max_f32_e32 v132, v132, v132
	s_waitcnt lgkmcnt(0)
	v_max_f32_e32 v133, v133, v133
	v_max_f32_e32 v132, v132, v133
	v_xor_b32_e32 v133, 32, v251
	v_cmp_lt_i32_e32 vcc, v133, v134
	s_nop 1
	v_cndmask_b32_e32 v133, v251, v133, vcc
	v_lshlrev_b32_e32 v133, 2, v133
	ds_bpermute_b32 v133, v133, v132
	s_waitcnt lgkmcnt(0)
	v_max3_f32 v133, v132, v133, 0
	v_exp_f32_e64 v132, -v133
	v_add_f32_e32 v203, v203, v133
	v_sub_f32_e32 v124, v124, v133
	v_sub_f32_e32 v125, v125, v133
	v_mul_f32_e32 v200, v200, v132
	v_pk_mul_f32 v[62:63], v[62:63], v[132:133] op_sel_hi:[1,0]
	v_pk_mul_f32 v[60:61], v[60:61], v[132:133] op_sel_hi:[1,0]
	v_pk_mul_f32 v[50:51], v[50:51], v[132:133] op_sel_hi:[1,0]
	v_pk_mul_f32 v[48:49], v[48:49], v[132:133] op_sel_hi:[1,0]
	v_pk_mul_f32 v[74:75], v[74:75], v[132:133] op_sel_hi:[1,0]
	v_pk_mul_f32 v[72:73], v[72:73], v[132:133] op_sel_hi:[1,0]
	v_pk_mul_f32 v[70:71], v[70:71], v[132:133] op_sel_hi:[1,0]
	v_pk_mul_f32 v[68:69], v[68:69], v[132:133] op_sel_hi:[1,0]
	v_sub_f32_e32 v126, v126, v133
	v_sub_f32_e32 v127, v127, v133
	v_sub_f32_e32 v128, v128, v133
	v_sub_f32_e32 v129, v129, v133
	v_sub_f32_e32 v130, v130, v133
	v_sub_f32_e32 v131, v131, v133
	v_sub_f32_e32 v138, v138, v133
	v_sub_f32_e32 v139, v139, v133
	v_sub_f32_e32 v140, v140, v133
	v_sub_f32_e32 v141, v141, v133
	v_sub_f32_e32 v144, v144, v133
	v_sub_f32_e32 v145, v145, v133
	v_sub_f32_e32 v146, v146, v133
	v_sub_f32_e32 v147, v147, v133

; #define MFMA16(a, b, c) __builtin_amdgcn_mfma_f32_16x16x32_bf16((a), (b), (c), 0, 0, 0)
; DI void attn_phase(const Params& p, unsigned char* smem) {
;     ...
;                         for (int kk = 0; kk < 4; ++kk) {
;                             st[kk] = (f32x4){nm, nm, nm, nm};
; #pragma unroll
;                             for (int s = 0; s < 3; ++s) st[kk] = MFMA16(kf[kk][s], qf[qs][s], st[kk]);
;                         }
;                         float mx = fmaxf(fmaxf(st[0][0], st[0][1]), fmaxf(st[0][2], st[0][3]));
; #pragma unroll
;                         for (int kk = 1; kk < 4; ++kk) mx = fmaxf(mx, fmaxf(fmaxf(st[kk][0], st[kk][1]), fmaxf(st[kk][2], st[kk][3])));
;                         const bool first = (st_ == 0 && hf == 0);
;                         if (first || __any(mx > 6.f)) {
;                             mx = fmaxf(mx, __shfl_xor(mx, 16)); mx = fmaxf(mx, __shfl_xor(mx, 32));
;                             const float shift = first ? mx : fmaxf(mx, 0.f);
;                             const float al = first ? 1.f : __builtin_amdgcn_exp2f(-shift);
;                             mrow[qs] += shift; lrow[qs] *= al;
; #pragma unroll
;                             for (int dt = 0; dt < 4; ++dt) ot[dt][qs] *= al;
; #pragma unroll
;                             for (int kk = 0; kk < 4; ++kk)
; #pragma unroll
;                                 for (int e = 0; e < 4; ++e) st[kk][e] -= shift;
;                         }
.LBB0_943:
	s_add_i32 s14, s43, -1
	s_and_b32 s18, s14, 1
	s_mul_i32 s14, s18, 0xb400
	s_add_i32 s19, s14, 16
	v_add_u32_e32 v76, s19, v164
	v_cmp_lt_i32_e32 vcc, s44, v230
	v_add_u32_e32 v231, v76, v218
	s_and_saveexec_b64 s[14:15], vcc
	s_cbranch_execz .LBB0_949
	v_xor_b32_e32 v132, 0x80000000, v203
	v_mov_b32_e32 v133, v132
	v_mov_b32_e32 v134, v132
	v_mov_b32_e32 v135, v132
	ds_read_b128 v[112:115], v231
	ds_read_b128 v[116:119], v231 offset:64
	ds_read_b128 v[120:123], v231 offset:128
	ds_read_b128 v[100:103], v231 offset:3584
	ds_read_b128 v[104:107], v231 offset:3648
	ds_read_b128 v[108:111], v231 offset:3712
	ds_read_b128 v[96:99], v231 offset:7168
	ds_read_b128 v[92:95], v231 offset:7232
	ds_read_b128 v[88:91], v231 offset:7296
	ds_read_b128 v[84:87], v231 offset:10752
	ds_read_b128 v[80:83], v231 offset:10816
	ds_read_b128 v[76:79], v231 offset:10880
	s_waitcnt lgkmcnt(11)
	v_mfma_f32_16x16x32_bf16 v[124:127], v[112:115], v[4:7], v[132:135]
	s_waitcnt lgkmcnt(8)
	v_mfma_f32_16x16x32_bf16 v[128:131], v[100:103], v[4:7], v[132:135]
	v_mfma_f32_16x16x32_bf16 v[124:127], v[116:119], v[0:3], v[124:127]
	s_waitcnt lgkmcnt(5)
	v_mfma_f32_16x16x32_bf16 v[136:139], v[96:99], v[4:7], v[132:135]
	s_waitcnt lgkmcnt(2)
	v_mfma_f32_16x16x32_bf16 v[132:135], v[84:87], v[4:7], v[132:135]
	v_mfma_f32_16x16x32_bf16 v[128:131], v[104:107], v[0:3], v[128:131]
	v_mfma_f32_16x16x32_bf16 v[124:127], v[120:123], v[12:15], v[124:127]
	s_waitcnt lgkmcnt(1)
	v_mfma_f32_16x16x32_bf16 v[132:135], v[80:83], v[0:3], v[132:135]
	v_mfma_f32_16x16x32_bf16 v[136:139], v[92:95], v[0:3], v[136:139]
	v_mfma_f32_16x16x32_bf16 v[128:131], v[108:111], v[12:15], v[128:131]
	s_waitcnt lgkmcnt(0)
	v_mfma_f32_16x16x32_bf16 v[144:147], v[76:79], v[12:15], v[132:135]
	s_nop 3
	v_max3_f32 v132, v124, v125, v126
	v_mfma_f32_16x16x32_bf16 v[138:141], v[88:91], v[12:15], v[136:139]
	v_max3_f32 v133, v127, v128, v129
	v_max3_f32 v132, v132, v130, v131
	v_max3_f32 v134, v144, v145, v146
	v_max3_f32 v132, v132, v133, v134
	s_nop 3
	v_max3_f32 v133, v138, v139, v140
	v_max3_f32 v132, v132, v133, v141
	v_max_f32_e32 v132, v132, v147
	v_cmp_lt_f32_e32 vcc, s34, v132
	s_cbranch_vccz .LBB0_946
	v_and_b32_e32 v134, 64, v251
	v_xor_b32_e32 v133, 16, v251
	v_add_u32_e32 v134, 64, v134
	v_cmp_lt_i32_e32 vcc, v133, v134
	s_nop 1
	v_cndmask_b32_e32 v133, v251, v133, vcc
	v_lshlrev_b32_e32 v133, 2, v133
	ds_bpermute_b32 v133, v133, v132
	v_max_f32_e32 v132, v132, v132
	s_waitcnt lgkmcnt(0)
	v_max_f32_e32 v133, v133, v133
	v_max_f32_e32 v132, v132, v133
	v_xor_b32_e32 v133, 32, v251
	v_cmp_lt_i32_e32 vcc, v133, v134
	s_nop 1
	v_cndmask_b32_e32 v133, v251, v133, vcc
	v_lshlrev_b32_e32 v133, 2, v133
	ds_bpermute_b32 v133, v133, v132
	s_waitcnt lgkmcnt(0)
	v_max3_f32 v133, v132, v133, 0
	v_exp_f32_e64 v132, -v133
	v_add_f32_e32 v203, v203, v133
	v_sub_f32_e32 v124, v124, v133
	v_sub_f32_e32 v125, v125, v133
	v_mul_f32_e32 v200, v200, v132
	v_pk_mul_f32 v[62:63], v[62:63], v[132:133] op_sel_hi:[1,0]
	v_pk_mul_f32 v[60:61], v[60:61], v[132:133] op_sel_hi:[1,0]
	v_pk_mul_f32 v[50:51], v[50:51], v[132:133] op_sel_hi:[1,0]
	v_pk_mul_f32 v[48:49], v[48:49], v[132:133] op_sel_hi:[1,0]
	v_pk_mul_f32 v[74:75], v[74:75], v[132:133] op_sel_hi:[1,0]
	v_pk_mul_f32 v[72:73], v[72:73], v[132:133] op_sel_hi:[1,0]
	v_pk_mul_f32 v[70:71], v[70:71], v[132:133] op_sel_hi:[1,0]
	v_pk_mul_f32 v[68:69], v[68:69], v[132:133] op_sel_hi:[1,0]
	v_sub_f32_e32 v126, v126, v133
	v_sub_f32_e32 v127, v127, v133
	v_sub_f32_e32 v128, v128, v133
	v_sub_f32_e32 v129, v129, v133
	v_sub_f32_e32 v130, v130, v133
	v_sub_f32_e32 v131, v131, v133
	v_sub_f32_e32 v138, v138, v133
	v_sub_f32_e32 v139, v139, v133
	v_sub_f32_e32 v140, v140, v133
	v_sub_f32_e32 v141, v141, v133
	v_sub_f32_e32 v144, v144, v133
	v_sub_f32_e32 v145, v145, v133
	v_sub_f32_e32 v146, v146, v133
	v_sub_f32_e32 v147, v147, v133
; DI void attn_phase(const Params& p, unsigned char* smem) {
;     ...
;                         for (int kk = 0; kk < 4; ++kk) {
;                             st[kk] = (f32x4){nm, nm, nm, nm};
; #pragma unroll
;                             for (int s = 0; s < 3; ++s) st[kk] = MFMA16(kf[kk][s], qf[qs][s], st[kk]);
;                         }
;                         float mx = fmaxf(fmaxf(st[0][0], st[0][1]), fmaxf(st[0][2], st[0][3]));
; #pragma unroll
;                         for (int kk = 1; kk < 4; ++kk) mx = fmaxf(mx, fmaxf(fmaxf(st[kk][0], st[kk][1]), fmaxf(st[kk][2], st[kk][3])));
;                         const bool first = (st_ == 0 && hf == 0);
;                         if (first || __any(mx > 6.f)) {
;                             mx = fmaxf(mx, __shfl_xor(mx, 16)); mx = fmaxf(mx, __shfl_xor(mx, 32));
;                             const float shift = first ? mx : fmaxf(mx, 0.f);
;                             const float al = first ? 1.f : __builtin_amdgcn_exp2f(-shift);
;                             mrow[qs] += shift; lrow[qs] *= al;
; #pragma unroll
;                             for (int dt = 0; dt < 4; ++dt) ot[dt][qs] *= al;
; #pragma unroll
;                             for (int kk = 0; kk < 4; ++kk)
; #pragma unroll
;                                 for (int e = 0; e < 4; ++e) st[kk][e] -= shift;
;                         }
;                         float rs = 0.f;
; #pragma unroll
;                         for (int kk = 0; kk < 4; ++kk)
; #pragma unroll
;                             for (int e = 0; e < 4; ++e) { const float pv = __builtin_amdgcn_exp2f(st[kk][e]); st[kk][e] = pv; rs += pv; }
;                         lrow[qs] += rs;
; #pragma unroll
;                         for (int s2 = 0; s2 < 2; ++s2) {
;                             uint4 u; u.x = pack2(st[2 * s2][0], st[2 * s2][1]); u.y = pack2(st[2 * s2][2], st[2 * s2][3]);
;                             u.z = pack2(st[2 * s2 + 1][0], st[2 * s2 + 1][1]); u.w = pack2(st[2 * s2 + 1][2], st[2 * s2 + 1][3]);
;                             const bf16x8 pf = asbf(u);
; #pragma unroll
;                             for (int dt = 0; dt < 4; ++dt) {
;                                 const uint2 a = *(const uint2*)(sV + (16 * dt + fr) * VST + 32 * s2 + 4 * g), b = *(const uint2*)(sV + (16 * dt + fr) * VST + 32 * s2 + 16 + 4 * g);
.LBB0_946:
	v_lshlrev_b32_e32 v136, 1, v217
	v_add3_u32 v132, s19, v219, v136
	v_exp_f32_e32 v236, v128
	v_add_u32_e32 v142, 0x7000, v132
	v_add3_u32 v128, s19, v220, v136
	v_add3_u32 v132, s19, v221, v136
	v_add3_u32 v136, s19, v222, v136
	v_add_u32_e32 v152, 0x7000, v128
	v_add_u32_e32 v153, 0x7000, v132
	v_add_u32_e32 v154, 0x7000, v136
	v_exp_f32_e32 v232, v124
	v_exp_f32_e32 v233, v125
	v_exp_f32_e32 v234, v126
	v_exp_f32_e32 v235, v127
	v_exp_f32_e32 v237, v129
	v_exp_f32_e32 v238, v130
	v_exp_f32_e32 v239, v131
	ds_read2_b64 v[124:127], v142 offset1:4
	v_exp_f32_e32 v240, v138
	ds_read2_b64 v[128:131], v152 offset1:4
	ds_read2_b64 v[132:135], v153 offset1:4
	v_exp_f32_e32 v241, v139
	ds_read2_b64 v[136:139], v154 offset1:4
	v_cvt_pk_bf16_f32 v148, v232, v233
	v_cvt_pk_bf16_f32 v149, v234, v235
	v_cvt_pk_bf16_f32 v150, v236, v237
	v_cvt_pk_bf16_f32 v151, v238, v239
	v_exp_f32_e32 v242, v140
	v_exp_f32_e32 v243, v141
	s_waitcnt lgkmcnt(3)
	v_mfma_f32_16x16x32_bf16 v[60:63], v[124:127], v[148:151], v[60:63]
	v_exp_f32_e32 v244, v144
	ds_read2_b64 v[140:143], v142 offset0:8 offset1:12
	v_exp_f32_e32 v245, v145
	s_waitcnt lgkmcnt(3)
	v_mfma_f32_16x16x32_bf16 v[48:51], v[128:131], v[148:151], v[48:51]
	v_exp_f32_e32 v246, v146
	v_exp_f32_e32 v247, v147
	ds_read2_b64 v[144:147], v152 offset0:8 offset1:12
	s_waitcnt lgkmcnt(3)
	v_mfma_f32_16x16x32_bf16 v[72:75], v[132:135], v[148:151], v[72:75]
	v_cvt_pk_bf16_f32 v158, v240, v241
	v_cvt_pk_bf16_f32 v159, v242, v243
	v_cvt_pk_bf16_f32 v160, v244, v245
	s_waitcnt lgkmcnt(2)
	v_mfma_f32_16x16x32_bf16 v[68:71], v[136:139], v[148:151], v[68:71]
	ds_read2_b64 v[148:151], v153 offset0:8 offset1:12
	ds_read2_b64 v[152:155], v154 offset0:8 offset1:12
	v_cvt_pk_bf16_f32 v161, v246, v247
	s_waitcnt lgkmcnt(3)
	s_nop 0
	v_mfma_f32_16x16x32_bf16 v[60:63], v[140:143], v[158:161], v[60:63]
	s_waitcnt lgkmcnt(2)
	v_mfma_f32_16x16x32_bf16 v[48:51], v[144:147], v[158:161], v[48:51]
	s_waitcnt lgkmcnt(1)
	v_mfma_f32_16x16x32_bf16 v[72:75], v[148:151], v[158:161], v[72:75]
	s_waitcnt lgkmcnt(0)
	v_mfma_f32_16x16x32_bf16 v[68:71], v[152:155], v[158:161], v[68:71]
	v_xor_b32_e32 v158, 0x80000000, v202
	v_mov_b32_e32 v159, v158
	v_mov_b32_e32 v160, v158
	v_mov_b32_e32 v161, v158
	s_nop 1
	v_mfma_f32_16x16x32_bf16 v[100:103], v[100:103], v[8:11], v[158:161]
	v_mfma_f32_16x16x32_bf16 v[112:115], v[112:115], v[8:11], v[158:161]
	v_mfma_f32_16x16x32_bf16 v[96:99], v[96:99], v[8:11], v[158:161]
	v_mfma_f32_16x16x32_bf16 v[84:87], v[84:87], v[8:11], v[158:161]
	v_mfma_f32_16x16x32_bf16 v[100:103], v[104:107], v[20:23], v[100:103]
	v_mfma_f32_16x16x32_bf16 v[112:115], v[116:119], v[20:23], v[112:115]
	v_mfma_f32_16x16x32_bf16 v[92:95], v[92:95], v[20:23], v[96:99]
	v_mfma_f32_16x16x32_bf16 v[80:83], v[80:83], v[20:23], v[84:87]
	v_mfma_f32_16x16x32_bf16 v[100:103], v[108:111], v[16:19], v[100:103]
	v_mfma_f32_16x16x32_bf16 v[112:115], v[120:123], v[16:19], v[112:115]
	v_mfma_f32_16x16x32_bf16 v[88:91], v[88:91], v[16:19], v[92:95]
	v_mfma_f32_16x16x32_bf16 v[76:79], v[76:79], v[16:19], v[80:83]
	s_nop 4
	v_max3_f32 v93, v100, v101, v102
	v_max3_f32 v94, v103, v112, v113
	v_max3_f32 v96, v114, v115, v88
	v_max3_f32 v93, v93, v94, v96
	v_max3_f32 v94, v89, v90, v91
	v_max3_f32 v96, v76, v77, v78
	v_max3_f32 v93, v93, v94, v96
	v_max_f32_e32 v80, v93, v79
	v_cmp_lt_f32_e32 vcc, s34, v80
	s_cbranch_vccz .LBB0_948
	v_and_b32_e32 v82, 64, v251
	v_xor_b32_e32 v81, 16, v251
	v_add_u32_e32 v82, 64, v82
	v_cmp_lt_i32_e32 vcc, v81, v82
	s_nop 1
	v_cndmask_b32_e32 v81, v251, v81, vcc
	v_lshlrev_b32_e32 v81, 2, v81
	ds_bpermute_b32 v81, v81, v80
	v_max_f32_e32 v80, v80, v80
	s_waitcnt lgkmcnt(0)
	v_max_f32_e32 v81, v81, v81
	v_max_f32_e32 v80, v80, v81
	v_xor_b32_e32 v81, 32, v251
	v_cmp_lt_i32_e32 vcc, v81, v82
	s_nop 1
	v_cndmask_b32_e32 v81, v251, v81, vcc
	v_lshlrev_b32_e32 v81, 2, v81
	ds_bpermute_b32 v81, v81, v80
	s_waitcnt lgkmcnt(0)
	v_max3_f32 v81, v80, v81, 0
	v_exp_f32_e64 v80, -v81
	v_add_f32_e32 v202, v202, v81
	v_sub_f32_e32 v112, v112, v81
	v_sub_f32_e32 v113, v113, v81
	v_mul_f32_e32 v201, v201, v80
	v_pk_mul_f32 v[66:67], v[66:67], v[80:81] op_sel_hi:[1,0]
	v_pk_mul_f32 v[64:65], v[64:65], v[80:81] op_sel_hi:[1,0]
	v_pk_mul_f32 v[58:59], v[58:59], v[80:81] op_sel_hi:[1,0]
	v_pk_mul_f32 v[56:57], v[56:57], v[80:81] op_sel_hi:[1,0]
	v_pk_mul_f32 v[54:55], v[54:55], v[80:81] op_sel_hi:[1,0]
	v_pk_mul_f32 v[52:53], v[52:53], v[80:81] op_sel_hi:[1,0]
	v_pk_mul_f32 v[46:47], v[46:47], v[80:81] op_sel_hi:[1,0]
	v_pk_mul_f32 v[44:45], v[44:45], v[80:81] op_sel_hi:[1,0]
	v_sub_f32_e32 v114, v114, v81
	v_sub_f32_e32 v115, v115, v81
	v_sub_f32_e32 v100, v100, v81
	v_sub_f32_e32 v101, v101, v81
	v_sub_f32_e32 v102, v102, v81
	v_sub_f32_e32 v103, v103, v81
	v_sub_f32_e32 v88, v88, v81
	v_sub_f32_e32 v89, v89, v81
	v_sub_f32_e32 v90, v90, v81
	v_sub_f32_e32 v91, v91, v81
	v_sub_f32_e32 v76, v76, v81
	v_sub_f32_e32 v77, v77, v81
	v_sub_f32_e32 v78, v78, v81
	v_sub_f32_e32 v79, v79, v81

; #define MFMA16(a, b, c) __builtin_amdgcn_mfma_f32_16x16x32_bf16((a), (b), (c), 0, 0, 0)
; DI void attn_phase(const Params& p, unsigned char* smem) {
;     ...
;                 if (2 * st_ + hf < wtiles) {
;                     const bf16_t* sK = sbuf + cur * BUF + hf * 64 * KST; const bf16_t* sV = sbuf + cur * BUF + 128 * KST + hf * 64;
;                     bf16x8 kf[4][3];
; #pragma unroll
;                     for (int kk = 0; kk < 4; ++kk)
; #pragma unroll
;                         for (int s = 0; s < 3; ++s) kf[kk][s] = *(const bf16x8*)(sK + (16 * kk + fr) * KST + 32 * s + 8 * g);
; #pragma unroll
;                     for (int qs = 0; qs < 2; ++qs) {
;                         f32x4 st[4];
;                         const float nm = -mrow[qs];
; #pragma unroll
;                         for (int kk = 0; kk < 4; ++kk) {
;                             st[kk] = (f32x4){nm, nm, nm, nm};
; #pragma unroll
;                             for (int s = 0; s < 3; ++s) st[kk] = MFMA16(kf[kk][s], qf[qs][s], st[kk]);
;                         }
;                         float mx = fmaxf(fmaxf(st[0][0], st[0][1]), fmaxf(st[0][2], st[0][3]));
; #pragma unroll
;                         for (int kk = 1; kk < 4; ++kk) mx = fmaxf(mx, fmaxf(fmaxf(st[kk][0], st[kk][1]), fmaxf(st[kk][2], st[kk][3])));
;                         const bool first = (st_ == 0 && hf == 0);
;                         if (first || __any(mx > 6.f)) {
;                             mx = fmaxf(mx, __shfl_xor(mx, 16)); mx = fmaxf(mx, __shfl_xor(mx, 32));
;                             const float shift = first ? mx : fmaxf(mx, 0.f);
;                             const float al = first ? 1.f : __builtin_amdgcn_exp2f(-shift);
;                             mrow[qs] += shift; lrow[qs] *= al;
; #pragma unroll
;                             for (int dt = 0; dt < 4; ++dt) ot[dt][qs] *= al;
; #pragma unroll
;                             for (int kk = 0; kk < 4; ++kk)
; #pragma unroll
;                                 for (int e = 0; e < 4; ++e) st[kk][e] -= shift;
;                         }
.LBB0_949:
	s_or_b64 exec, exec, s[14:15]
	s_add_i32 s14, s44, 1
	v_cmp_lt_i32_e32 vcc, s14, v230
	s_and_saveexec_b64 s[14:15], vcc
	s_cbranch_execz .LBB0_955
	v_xor_b32_e32 v132, 0x80000000, v203
	v_mov_b32_e32 v133, v132
	v_mov_b32_e32 v134, v132
	v_mov_b32_e32 v135, v132
	ds_read_b128 v[112:115], v231 offset:14336
	ds_read_b128 v[116:119], v231 offset:14400
	ds_read_b128 v[120:123], v231 offset:14464
	ds_read_b128 v[100:103], v231 offset:17920
	ds_read_b128 v[104:107], v231 offset:17984
	ds_read_b128 v[108:111], v231 offset:18048
	ds_read_b128 v[96:99], v231 offset:21504
	ds_read_b128 v[92:95], v231 offset:21568
	ds_read_b128 v[88:91], v231 offset:21632
	ds_read_b128 v[84:87], v231 offset:25088
	ds_read_b128 v[80:83], v231 offset:25152
	ds_read_b128 v[76:79], v231 offset:25216
	s_waitcnt lgkmcnt(11)
	v_mfma_f32_16x16x32_bf16 v[124:127], v[112:115], v[4:7], v[132:135]
	s_waitcnt lgkmcnt(8)
	v_mfma_f32_16x16x32_bf16 v[128:131], v[100:103], v[4:7], v[132:135]
	v_mfma_f32_16x16x32_bf16 v[124:127], v[116:119], v[0:3], v[124:127]
	s_waitcnt lgkmcnt(5)
	v_mfma_f32_16x16x32_bf16 v[136:139], v[96:99], v[4:7], v[132:135]
	s_waitcnt lgkmcnt(2)
	v_mfma_f32_16x16x32_bf16 v[132:135], v[84:87], v[4:7], v[132:135]
	v_mfma_f32_16x16x32_bf16 v[128:131], v[104:107], v[0:3], v[128:131]
	v_mfma_f32_16x16x32_bf16 v[124:127], v[120:123], v[12:15], v[124:127]
	s_waitcnt lgkmcnt(1)
	v_mfma_f32_16x16x32_bf16 v[132:135], v[80:83], v[0:3], v[132:135]
	v_mfma_f32_16x16x32_bf16 v[136:139], v[92:95], v[0:3], v[136:139]
	v_mfma_f32_16x16x32_bf16 v[128:131], v[108:111], v[12:15], v[128:131]
	s_waitcnt lgkmcnt(0)
	v_mfma_f32_16x16x32_bf16 v[144:147], v[76:79], v[12:15], v[132:135]
	s_nop 3
	v_max3_f32 v132, v124, v125, v126
	v_mfma_f32_16x16x32_bf16 v[138:141], v[88:91], v[12:15], v[136:139]
	v_max3_f32 v133, v127, v128, v129
	v_max3_f32 v132, v132, v130, v131
	v_max3_f32 v134, v144, v145, v146
	v_max3_f32 v132, v132, v133, v134
	s_nop 3
	v_max3_f32 v133, v138, v139, v140
	v_max3_f32 v132, v132, v133, v141
	v_max_f32_e32 v132, v132, v147
	v_cmp_lt_f32_e32 vcc, s34, v132
	s_cbranch_vccz .LBB0_952
	v_and_b32_e32 v134, 64, v251
	v_xor_b32_e32 v133, 16, v251
	v_add_u32_e32 v134, 64, v134
	v_cmp_lt_i32_e32 vcc, v133, v134
	s_nop 1
	v_cndmask_b32_e32 v133, v251, v133, vcc
	v_lshlrev_b32_e32 v133, 2, v133
	ds_bpermute_b32 v133, v133, v132
	v_max_f32_e32 v132, v132, v132
	s_waitcnt lgkmcnt(0)
	v_max_f32_e32 v133, v133, v133
	v_max_f32_e32 v132, v132, v133
	v_xor_b32_e32 v133, 32, v251
	v_cmp_lt_i32_e32 vcc, v133, v134
	s_nop 1
	v_cndmask_b32_e32 v133, v251, v133, vcc
	v_lshlrev_b32_e32 v133, 2, v133
	ds_bpermute_b32 v133, v133, v132
	s_waitcnt lgkmcnt(0)
	v_max3_f32 v133, v132, v133, 0
	v_exp_f32_e64 v132, -v133
	v_add_f32_e32 v203, v203, v133
	v_sub_f32_e32 v124, v124, v133
	v_sub_f32_e32 v125, v125, v133
	v_mul_f32_e32 v200, v200, v132
	v_pk_mul_f32 v[62:63], v[62:63], v[132:133] op_sel_hi:[1,0]
	v_pk_mul_f32 v[60:61], v[60:61], v[132:133] op_sel_hi:[1,0]
	v_pk_mul_f32 v[50:51], v[50:51], v[132:133] op_sel_hi:[1,0]
	v_pk_mul_f32 v[48:49], v[48:49], v[132:133] op_sel_hi:[1,0]
	v_pk_mul_f32 v[74:75], v[74:75], v[132:133] op_sel_hi:[1,0]
	v_pk_mul_f32 v[72:73], v[72:73], v[132:133] op_sel_hi:[1,0]
	v_pk_mul_f32 v[70:71], v[70:71], v[132:133] op_sel_hi:[1,0]
	v_pk_mul_f32 v[68:69], v[68:69], v[132:133] op_sel_hi:[1,0]
	v_sub_f32_e32 v126, v126, v133
	v_sub_f32_e32 v127, v127, v133
	v_sub_f32_e32 v128, v128, v133
	v_sub_f32_e32 v129, v129, v133
	v_sub_f32_e32 v130, v130, v133
	v_sub_f32_e32 v131, v131, v133
	v_sub_f32_e32 v138, v138, v133
	v_sub_f32_e32 v139, v139, v133
	v_sub_f32_e32 v140, v140, v133
	v_sub_f32_e32 v141, v141, v133
	v_sub_f32_e32 v144, v144, v133
	v_sub_f32_e32 v145, v145, v133
	v_sub_f32_e32 v146, v146, v133
	v_sub_f32_e32 v147, v147, v133
; DI void attn_phase(const Params& p, unsigned char* smem) {
;     ...
;                         for (int kk = 0; kk < 4; ++kk) {
;                             st[kk] = (f32x4){nm, nm, nm, nm};
; #pragma unroll
;                             for (int s = 0; s < 3; ++s) st[kk] = MFMA16(kf[kk][s], qf[qs][s], st[kk]);
;                         }
;                         float mx = fmaxf(fmaxf(st[0][0], st[0][1]), fmaxf(st[0][2], st[0][3]));
; #pragma unroll
;                         for (int kk = 1; kk < 4; ++kk) mx = fmaxf(mx, fmaxf(fmaxf(st[kk][0], st[kk][1]), fmaxf(st[kk][2], st[kk][3])));
;                         const bool first = (st_ == 0 && hf == 0);
;                         if (first || __any(mx > 6.f)) {
;                             mx = fmaxf(mx, __shfl_xor(mx, 16)); mx = fmaxf(mx, __shfl_xor(mx, 32));
;                             const float shift = first ? mx : fmaxf(mx, 0.f);
;                             const float al = first ? 1.f : __builtin_amdgcn_exp2f(-shift);
;                             mrow[qs] += shift; lrow[qs] *= al;
; #pragma unroll
;                             for (int dt = 0; dt < 4; ++dt) ot[dt][qs] *= al;
; #pragma unroll
;                             for (int kk = 0; kk < 4; ++kk)
; #pragma unroll
;                                 for (int e = 0; e < 4; ++e) st[kk][e] -= shift;
;                         }
;                         float rs = 0.f;
; #pragma unroll
;                         for (int kk = 0; kk < 4; ++kk)
; #pragma unroll
;                             for (int e = 0; e < 4; ++e) { const float pv = __builtin_amdgcn_exp2f(st[kk][e]); st[kk][e] = pv; rs += pv; }
;                         lrow[qs] += rs;
; #pragma unroll
;                         for (int s2 = 0; s2 < 2; ++s2) {
;                             uint4 u; u.x = pack2(st[2 * s2][0], st[2 * s2][1]); u.y = pack2(st[2 * s2][2], st[2 * s2][3]);
;                             u.z = pack2(st[2 * s2 + 1][0], st[2 * s2 + 1][1]); u.w = pack2(st[2 * s2 + 1][2], st[2 * s2 + 1][3]);
;                             const bf16x8 pf = asbf(u);
; #pragma unroll
;                             for (int dt = 0; dt < 4; ++dt) {
;                                 const uint2 a = *(const uint2*)(sV + (16 * dt + fr) * VST + 32 * s2 + 4 * g), b = *(const uint2*)(sV + (16 * dt + fr) * VST + 32 * s2 + 16 + 4 * g);
.LBB0_952:
	v_lshlrev_b32_e32 v136, 1, v217
	v_add3_u32 v132, s19, v219, v136
	v_exp_f32_e32 v235, v128
	v_add_u32_e32 v142, 0x7000, v132
	v_add3_u32 v128, s19, v220, v136
	v_add3_u32 v132, s19, v221, v136
	v_add3_u32 v136, s19, v222, v136
	v_add_u32_e32 v152, 0x7000, v128
	v_add_u32_e32 v153, 0x7000, v132
	v_add_u32_e32 v154, 0x7000, v136
	v_exp_f32_e32 v231, v124
	v_exp_f32_e32 v232, v125
	v_exp_f32_e32 v233, v126
	v_exp_f32_e32 v234, v127
	v_exp_f32_e32 v236, v129
	v_exp_f32_e32 v237, v130
	v_exp_f32_e32 v238, v131
	ds_read2_b64 v[124:127], v142 offset0:16 offset1:20
	v_exp_f32_e32 v239, v138
	ds_read2_b64 v[128:131], v152 offset0:16 offset1:20
	ds_read2_b64 v[132:135], v153 offset0:16 offset1:20
	v_exp_f32_e32 v240, v139
	ds_read2_b64 v[136:139], v154 offset0:16 offset1:20
	v_cvt_pk_bf16_f32 v148, v231, v232
	v_cvt_pk_bf16_f32 v149, v233, v234
	v_cvt_pk_bf16_f32 v150, v235, v236
	v_cvt_pk_bf16_f32 v151, v237, v238
	v_exp_f32_e32 v241, v140
	v_exp_f32_e32 v242, v141
	s_waitcnt lgkmcnt(3)
	v_mfma_f32_16x16x32_bf16 v[60:63], v[124:127], v[148:151], v[60:63]
	v_exp_f32_e32 v243, v144
	ds_read2_b64 v[140:143], v142 offset0:24 offset1:28
	v_exp_f32_e32 v244, v145
	s_waitcnt lgkmcnt(3)
	v_mfma_f32_16x16x32_bf16 v[48:51], v[128:131], v[148:151], v[48:51]
	v_exp_f32_e32 v245, v146
	v_exp_f32_e32 v246, v147
	ds_read2_b64 v[144:147], v152 offset0:24 offset1:28
	s_waitcnt lgkmcnt(3)
	v_mfma_f32_16x16x32_bf16 v[72:75], v[132:135], v[148:151], v[72:75]
	v_cvt_pk_bf16_f32 v158, v239, v240
	v_cvt_pk_bf16_f32 v159, v241, v242
	v_cvt_pk_bf16_f32 v160, v243, v244
	s_waitcnt lgkmcnt(2)
	v_mfma_f32_16x16x32_bf16 v[68:71], v[136:139], v[148:151], v[68:71]
	ds_read2_b64 v[148:151], v153 offset0:24 offset1:28
	ds_read2_b64 v[152:155], v154 offset0:24 offset1:28
	v_cvt_pk_bf16_f32 v161, v245, v246
	s_waitcnt lgkmcnt(3)
	s_nop 0
	v_mfma_f32_16x16x32_bf16 v[60:63], v[140:143], v[158:161], v[60:63]
	s_waitcnt lgkmcnt(2)
	v_mfma_f32_16x16x32_bf16 v[48:51], v[144:147], v[158:161], v[48:51]
	s_waitcnt lgkmcnt(1)
	v_mfma_f32_16x16x32_bf16 v[72:75], v[148:151], v[158:161], v[72:75]
	s_waitcnt lgkmcnt(0)
	v_mfma_f32_16x16x32_bf16 v[68:71], v[152:155], v[158:161], v[68:71]
	v_xor_b32_e32 v158, 0x80000000, v202
	v_mov_b32_e32 v159, v158
	v_mov_b32_e32 v160, v158
	v_mov_b32_e32 v161, v158
	s_nop 1
	v_mfma_f32_16x16x32_bf16 v[100:103], v[100:103], v[8:11], v[158:161]
	v_mfma_f32_16x16x32_bf16 v[112:115], v[112:115], v[8:11], v[158:161]
	v_mfma_f32_16x16x32_bf16 v[96:99], v[96:99], v[8:11], v[158:161]
	v_mfma_f32_16x16x32_bf16 v[84:87], v[84:87], v[8:11], v[158:161]
	v_mfma_f32_16x16x32_bf16 v[100:103], v[104:107], v[20:23], v[100:103]
	v_mfma_f32_16x16x32_bf16 v[112:115], v[116:119], v[20:23], v[112:115]
	v_mfma_f32_16x16x32_bf16 v[92:95], v[92:95], v[20:23], v[96:99]
	v_mfma_f32_16x16x32_bf16 v[80:83], v[80:83], v[20:23], v[84:87]
	v_mfma_f32_16x16x32_bf16 v[100:103], v[108:111], v[16:19], v[100:103]
	v_mfma_f32_16x16x32_bf16 v[112:115], v[120:123], v[16:19], v[112:115]
	v_mfma_f32_16x16x32_bf16 v[88:91], v[88:91], v[16:19], v[92:95]
	v_mfma_f32_16x16x32_bf16 v[76:79], v[76:79], v[16:19], v[80:83]
	s_nop 4
	v_max3_f32 v93, v100, v101, v102
	v_max3_f32 v94, v103, v112, v113
	v_max3_f32 v96, v114, v115, v88
	v_max3_f32 v93, v93, v94, v96
	v_max3_f32 v94, v89, v90, v91
	v_max3_f32 v96, v76, v77, v78
	v_max3_f32 v93, v93, v94, v96
	v_max_f32_e32 v80, v93, v79
	v_cmp_lt_f32_e32 vcc, s34, v80
	s_cbranch_vccz .LBB0_954
	v_and_b32_e32 v82, 64, v251
	v_xor_b32_e32 v81, 16, v251
	v_add_u32_e32 v82, 64, v82
	v_cmp_lt_i32_e32 vcc, v81, v82
	s_nop 1
	v_cndmask_b32_e32 v81, v251, v81, vcc
	v_lshlrev_b32_e32 v81, 2, v81
	ds_bpermute_b32 v81, v81, v80
	v_max_f32_e32 v80, v80, v80
	s_waitcnt lgkmcnt(0)
	v_max_f32_e32 v81, v81, v81
	v_max_f32_e32 v80, v80, v81
	v_xor_b32_e32 v81, 32, v251
	v_cmp_lt_i32_e32 vcc, v81, v82
	s_nop 1
	v_cndmask_b32_e32 v81, v251, v81, vcc
	v_lshlrev_b32_e32 v81, 2, v81
	ds_bpermute_b32 v81, v81, v80
	s_waitcnt lgkmcnt(0)
	v_max3_f32 v81, v80, v81, 0
	v_exp_f32_e64 v80, -v81
	v_add_f32_e32 v202, v202, v81
	v_sub_f32_e32 v112, v112, v81
	v_sub_f32_e32 v113, v113, v81
	v_mul_f32_e32 v201, v201, v80
	v_pk_mul_f32 v[66:67], v[66:67], v[80:81] op_sel_hi:[1,0]
	v_pk_mul_f32 v[64:65], v[64:65], v[80:81] op_sel_hi:[1,0]
	v_pk_mul_f32 v[58:59], v[58:59], v[80:81] op_sel_hi:[1,0]
	v_pk_mul_f32 v[56:57], v[56:57], v[80:81] op_sel_hi:[1,0]
	v_pk_mul_f32 v[54:55], v[54:55], v[80:81] op_sel_hi:[1,0]
	v_pk_mul_f32 v[52:53], v[52:53], v[80:81] op_sel_hi:[1,0]
	v_pk_mul_f32 v[46:47], v[46:47], v[80:81] op_sel_hi:[1,0]
	v_pk_mul_f32 v[44:45], v[44:45], v[80:81] op_sel_hi:[1,0]
	v_sub_f32_e32 v114, v114, v81
	v_sub_f32_e32 v115, v115, v81
	v_sub_f32_e32 v100, v100, v81
	v_sub_f32_e32 v101, v101, v81
	v_sub_f32_e32 v102, v102, v81
	v_sub_f32_e32 v103, v103, v81
	v_sub_f32_e32 v88, v88, v81
	v_sub_f32_e32 v89, v89, v81
	v_sub_f32_e32 v90, v90, v81
	v_sub_f32_e32 v91, v91, v81
	v_sub_f32_e32 v76, v76, v81
	v_sub_f32_e32 v77, v77, v81
	v_sub_f32_e32 v78, v78, v81
	v_sub_f32_e32 v79, v79, v81
